# band item prologue: scale / table loads issued together, dependent work behind a counted wait (on top of the epilogue change)
# baseline (speedup 1.0000x reference)
; #define P_LUTD WSP(float, OFF_LUTD)
; DI int otid() { int t; asm volatile("v_mov_b32 %0, %1" : "=v"(t) : "v"((int)threadIdx.x)); __builtin_assume(t >= 0 && t < 256); return t; }
; #define BLOAD(k0) do { \
;     rk[0] = *(const u32x4*)(Kb + (size_t)((k0) + srow) * ldk + scc * 8); rk[1] = *(const u32x4*)(Kb + (size_t)((k0) + srow + 32) * ldk + scc * 8); \
;     rv[0] = *(const u32x4*)(Vb + (size_t)((k0) + srow) * ldk + scc * 8); rv[1] = *(const u32x4*)(Vb + (size_t)((k0) + srow + 32) * ldk + scc * 8); } while (0)
; template <int W, bool SINK>
; DI void attn_band_mfma(const bf16_t* Qb, size_t ldq, const bf16_t* Kb, const bf16_t* Vb, size_t ldk, int L, int i0,
;                        const float* lut_g, float sink2, bf16_t* outp, size_t ldo, float* lse_out, size_t ldl, char* smem) {
;     ...
;   const int tid = otid(), lane = tid & 63, wid = tid >> 6, r = lane & 31, h = lane >> 5;
;   __syncthreads();
;   for (int e = tid; e < LUTN; e += 256) sLut[e] = lut_g[e];
;   const int qi = i0 + wid * 32 + r;
;   bf16x8 qf[NS];
; #pragma unroll
;   for (int s = 0; s < NS; ++s) qf[s] = *(const bf16x8*)(Qb + (size_t)qi * ldq + 16 * s + 8 * h);
;   const int srow = tid >> 3, scc = tid & 7;
;   u32x4 rk[2], rv[2];
;     ...
;   const unsigned vb0 = (unsigned)(size_t)sVc + (unsigned)(((4 * h + ((lane & 15) >> 2)) * VLD + 16 * ((lane >> 4) & 1) + 4 * (lane & 3)) * 2);
;   f32x16 o0 = splat16(0.f), o1 = splat16(0.f);
;   float m_run = SINK ? sink2 : 0.f, l_run = (SINK && h == 0) ? 1.f : 0.f;
;   bool seen = SINK;
;   f32x16 negm = splat16(-m_run);
;   const int lo = (i0 == 0) ? W / 64 : 0, hi = (i0 + 128 >= L) ? NTW - W / 64 : NTW;
;   BLOAD(i0 - W + 64 * lo); BSTORE(0);
;   __syncthreads();
; DI void band_item(const Params& p, int l, int idx, char* smem) {
;     ...
;     const int it = idx - 3072, hq = it & 3, rem = it >> 2, b = 3 - (rem >> 6), qblk = rem & 63;
;     bf16_t* base = P_PROJ + (size_t)b * SEQ * PW;
;     attn_band_mfma<128, true>(base + C_DQ + hq * 64, PW, base + C_DK + (hq >> 1) * 64, base + C_DV + (hq >> 1) * 64, PW, SEQ, qblk * 128,
;                               P_LUTD + hq * 257, p.sink[l * 4 + hq] * LOG2E, base + C_GATE + 768 + hq * 64, PW, nullptr, 0, smem);
.LBB0_62:
	s_and_b32 s7, s11, 3
	s_and_b32 s6, s13, 3
	s_cmpk_gt_i32 s13, 0xbff
	s_mov_b64 s[0:1], -1
	s_cbranch_scc0 .LBB0_109
	s_mul_i32 s0, s6, 0x404
	v_readlane_b32 s22, v253, 12
	v_readlane_b32 s23, v253, 13
	s_add_u32 s0, s22, s0
	s_addc_u32 s1, s23, 0
	s_or_b32 s22, s6, s5
	s_lshl_b32 s22, s22, 2
	v_mov_b32_e32 v0, s22
	global_load_dword v67, v0, s[46:47]
	v_mov_b32 v0, v188
	s_nop 0
	v_lshl_add_u64 v[4:5], v[0:1], 2, s[0:1]
	s_barrier
	global_load_dword v64, v[4:5], off
	global_load_dword v65, v1, s[0:1] offset:1024
	v_lshlrev_b32_e32 v4, 2, v0
	v_lshlrev_b32_e32 v66, 2, v0
.LBB0_65:
	s_lshl_b32 s26, s13, 5
	s_and_b32 s0, s26, 0x7fe000
	s_sub_i32 s0, 0x1e000, s0
	s_mulk_i32 s0, 0x2600
	s_add_u32 s28, s28, s0
	s_addc_u32 s29, s29, 0
	s_lshl_b32 s30, s6, 6
	s_lshl_b32 s0, s6, 7
	s_add_u32 s24, s28, s0
	s_addc_u32 s25, s29, 0
	s_lshr_b32 s1, s12, 13
	s_mul_i32 s1, s1, 0x4c00000
	s_sub_i32 s94, 0x47400000, s1
	s_and_b32 s23, s12, 0x1f80
	s_lshl_b32 s1, s7, 6
	s_and_b32 s0, s30, 0x80
	s_and_b32 s22, s1, 0x80
	s_add_i32 s31, s23, 0xffffff80
	s_add_u32 s0, s28, s0
	v_lshrrev_b32_e32 v2, 1, v0
	s_addc_u32 s1, s29, 0
	s_and_b32 s27, s26, 0x1f80
	v_and_b32_e32 v11, 0x60, v2
	v_and_b32_e32 v10, 31, v0
	v_or_b32_e32 v12, s27, v11
	v_or_b32_e32 v2, v12, v10
	v_mul_u32_u24_e32 v132, 0x1300, v2
	v_bfe_u32 v5, v0, 5, 1
	v_lshlrev_b32_e32 v2, 1, v132
	v_mov_b32_e32 v3, v1
	v_lshl_add_u64 v[6:7], s[24:25], 0, v[2:3]
	v_lshlrev_b32_e32 v2, 4, v5
	v_lshl_add_u64 v[6:7], v[6:7], 0, v[2:3]
	s_mov_b64 s[24:25], 0x1600
	v_lshl_add_u64 v[8:9], v[6:7], 0, s[24:25]
	v_add_co_u32_e32 v6, vcc, s85, v6
	s_cmp_eq_u32 s27, 0
	s_nop 0
	v_addc_co_u32_e32 v7, vcc, 0, v7, vcc
	global_load_dwordx4 v[98:101], v[6:7], off offset:1536
	global_load_dwordx4 v[102:105], v[8:9], off offset:32
	global_load_dwordx4 v[106:109], v[8:9], off offset:64
	global_load_dwordx4 v[110:113], v[8:9], off offset:96
	v_lshlrev_b32_e32 v133, 2, v5
	v_lshrrev_b32_e32 v6, 2, v0
	s_cselect_b32 s26, 2, 0
	s_cmpk_eq_i32 s27, 0x1f80
	v_and_or_b32 v6, v6, 3, v133
	s_cselect_b32 s34, 4, 6
	s_lshl_b32 s35, s26, 6
	v_mul_u32_u24_e32 v6, 0x60, v6
	v_and_b32_e32 v7, 16, v0
	v_and_b32_e32 v4, 12, v4
	s_add_i32 s24, s27, s35
	v_lshrrev_b32_e32 v3, 3, v0
	v_or3_b32 v4, v6, v7, v4
	v_mov_b32_e32 v6, 0x4800
	s_addk_i32 s24, 0xff80
	v_lshl_add_u32 v139, v4, 1, v6
	v_or_b32_e32 v4, s24, v3
	v_mul_i32_i24_e32 v4, 0x1300, v4
	v_lshlrev_b32_e32 v6, 3, v0
	v_lshlrev_b32_e32 v130, 3, v5
	v_cmp_eq_u32_e32 vcc, 0, v5
	v_ashrrev_i32_e32 v5, 31, v4
	v_and_b32_e32 v8, 56, v6
	v_lshl_add_u64 v[4:5], v[4:5], 1, s[0:1]
	v_lshlrev_b32_e32 v6, 1, v8
	v_mov_b32_e32 v7, v1
	v_lshl_add_u64 v[4:5], v[4:5], 0, v[6:7]
	v_cndmask_b32_e64 v138, 0, 1.0, vcc
	v_add_co_u32_e32 v6, vcc, s85, v4
	s_mov_b32 s0, 0x4d000
	s_nop 0
	v_addc_co_u32_e32 v7, vcc, 0, v5, vcc
	v_add_co_u32_e32 v4, vcc, s0, v4
	global_load_dwordx4 v[114:117], v[6:7], off offset:2048
	s_nop 0
	v_addc_co_u32_e32 v5, vcc, 0, v5, vcc
	global_load_dwordx4 v[118:121], v[4:5], off offset:2048
	global_load_dwordx4 v[122:125], v[6:7], off offset:2304
	global_load_dwordx4 v[126:129], v[4:5], off offset:2304
	s_movk_i32 s0, 0x48
	v_mad_u32_u24 v4, v3, s0, v8
	v_or_b32_e32 v5, 32, v3
	v_mul_u32_u24_e32 v7, 24, v3
	v_lshlrev_b32_e32 v140, 1, v4
	v_add_u32_e32 v6, 0x900, v4
	v_add_lshl_u32 v142, v4, v7, 1
	v_mul_u32_u24_e32 v4, 24, v5
	s_movk_i32 s0, 0x90
	v_add_lshl_u32 v143, v6, v4, 1
	v_mad_u32_u24 v146, v10, s0, v2
	v_lshl_or_b32 v2, s26, 8, v2
	v_lshlrev_b32_e32 v4, 2, v10
	v_sub_u32_e32 v2, v2, v4
	v_lshlrev_b32_e32 v4, 1, v0
	v_and_b32_e32 v4, 0xffffff80, v4
	v_sub_u32_e32 v2, v2, v4
	s_add_i32 s0, s35, s23
	v_add_u32_e32 v147, 0xa800, v2
	v_sub_u32_e32 v2, v133, v10
	v_add_u32_e32 v4, s0, v3
	v_sub_u32_e32 v148, v2, v11
	v_subrev_u32_e32 v2, 32, v4
	s_movk_i32 s4, 0x2600
	v_lshlrev_b32_e32 v0, 4, v0
	v_mad_i64_i32 v[2:3], s[0:1], v2, s4, 0
	v_and_b32_e32 v0, 0x70, v0
	v_or3_b32 v2, v2, s22, v0
	v_lshl_add_u64 v[134:135], s[58:59], 0, v[2:3]
	v_subrev_u32_e32 v2, 64, v4
	v_mad_i64_i32 v[2:3], s[0:1], v2, s4, 0
	v_or3_b32 v2, v2, s22, v0
	v_mov_b32_e32 v14, v1
	v_mov_b32_e32 v15, v1
	s_waitcnt vmcnt(8)
	v_mul_f32_e32 v131, 0x3fb8aa3b, v67
	ds_write_b32 v66, v64 offset:43008
	ds_write_b32 v1, v65 offset:44032
	v_xor_b32_e32 v48, 0x80000000, v131
	v_lshlrev_b32_e32 v141, 1, v6
	v_add_u32_e32 v144, 0x9f, v12
	v_add_u32_e32 v145, 0xffffff41, v12
	v_lshl_add_u64 v[136:137], s[58:59], 0, v[2:3]
	v_mov_b32_e32 v0, v1
	v_mov_b32_e32 v2, v1
	v_mov_b32_e32 v3, v1
	v_mov_b32_e32 v4, v1
	v_mov_b32_e32 v5, v1
	v_mov_b32_e32 v6, v1
	v_mov_b32_e32 v7, v1
	v_mov_b32_e32 v8, v1
	v_mov_b32_e32 v9, v1
	v_mov_b32_e32 v10, v1
	v_mov_b32_e32 v11, v1
	v_mov_b32_e32 v12, v1
	v_mov_b32_e32 v13, v1
	v_mov_b64_e32 v[30:31], v[14:15]
	v_mov_b64_e32 v[46:47], v[14:15]
	v_mov_b64_e32 v[28:29], v[12:13]
	v_mov_b64_e32 v[26:27], v[10:11]
	v_mov_b64_e32 v[24:25], v[8:9]
	v_mov_b64_e32 v[22:23], v[6:7]
	v_mov_b64_e32 v[20:21], v[4:5]
	v_mov_b64_e32 v[18:19], v[2:3]
	v_mov_b64_e32 v[16:17], v[0:1]
	v_mov_b64_e32 v[44:45], v[12:13]
	v_mov_b64_e32 v[42:43], v[10:11]
	v_mov_b64_e32 v[40:41], v[8:9]
	v_mov_b64_e32 v[38:39], v[6:7]
	v_mov_b64_e32 v[36:37], v[4:5]
	v_mov_b64_e32 v[34:35], v[2:3]
	v_mov_b64_e32 v[32:33], v[0:1]
	v_mov_b32_e32 v49, v48
	v_mov_b32_e32 v50, v48
	v_mov_b32_e32 v51, v48
	v_mov_b32_e32 v52, v48
	v_mov_b32_e32 v53, v48
	v_mov_b32_e32 v54, v48
	v_mov_b32_e32 v55, v48
	v_mov_b32_e32 v56, v48
	v_mov_b32_e32 v57, v48
	v_mov_b32_e32 v58, v48
	v_mov_b32_e32 v59, v48
	v_mov_b32_e32 v60, v48
	v_mov_b32_e32 v61, v48
	v_mov_b32_e32 v62, v48
	v_mov_b32_e32 v63, v48
	s_waitcnt vmcnt(3)
	ds_write_b128 v140, v[114:117]
	s_waitcnt vmcnt(2)
	ds_write_b128 v140, v[118:121] offset:4608
	s_waitcnt vmcnt(1)
	ds_write_b128 v142, v[122:125] offset:18432
	s_waitcnt vmcnt(0)
	ds_write_b128 v143, v[126:129] offset:18432
	s_waitcnt lgkmcnt(0)
	s_barrier
